# combined: skip first-iteration K-loop waits after an epilogue, Res epilogue preamble loads in two batches, XCD barrier instead of the one cg grid sync
# speedup vs baseline: 1.0044x; 1.0044x over previous
; __device__ __forceinline__ unsigned xb_add(unsigned* p, unsigned v) { return __hip_atomic_fetch_add(p, v, __ATOMIC_RELAXED, __HIP_MEMORY_SCOPE_AGENT); }
; __device__ __forceinline__ void xcd_barrier(const XcdBarrier& b) {
;     asm volatile("s_waitcnt vmcnt(0)" ::: "memory");
;     __syncthreads();
;     if (threadIdx.x == 0) {
;         unsigned* bar = b.bar;
;         __builtin_amdgcn_s_waitcnt(0);
;         unsigned nloc = b.st[0], nx = b.st[1];
;         if (nloc == 0u) { xcd_barrier_complete(bar, b.x, nloc, nx); b.st[0] = nloc; b.st[1] = nx; }
;         const unsigned old = xb_add(&bar[XB_XSUB(b.x)], 1u);
;         const unsigned gen = old / nloc;
; __global__ void __launch_bounds__(512, 2) fwd_kernel(Params p) {
;     ...
;     for (int ph = p.ph_lo; ph < p.ph_hi; ++ph) {
;         if (ph > p.ph_lo) { if (ph == p.ph_lo + 1) cg::this_grid().sync(); else xcd_barrier(bar); }
.LBB0_9:
	s_cmp_le_i32 s38, s10
	s_cbranch_scc1 .LBB0_77
	v_readlane_b32 s0, v252, 2
	s_cmp_lg_u32 s38, s0
	s_mov_b64 s[28:29], -1
	s_waitcnt vmcnt(0)
	s_barrier
	s_mov_b64 s[28:29], exec
	v_readlane_b32 s0, v252, 0
	v_readlane_b32 s1, v252, 1
	s_and_b64 s[0:1], s[28:29], s[0:1]
	s_mov_b64 exec, s[0:1]
	s_cbranch_execz .LBB0_63
	v_readlane_b32 s0, v254, 32
	s_waitcnt vmcnt(0) expcnt(0) lgkmcnt(0)
	s_nop 0
	v_mov_b32_e32 v0, s0
	ds_read_b32 v2, v0
	v_readlane_b32 s0, v254, 33
	s_waitcnt lgkmcnt(0)
	v_cmp_ne_u32_e32 vcc, 0, v2
	v_mov_b32_e32 v0, s0
	ds_read_b32 v0, v0
	s_cbranch_vccnz .LBB0_27
	s_load_dwordx2 s[0:1], s[64:65], 0x0
	s_load_dword s9, s[64:65], 0x8
	s_waitcnt lgkmcnt(0)
	s_mul_i32 s0, s1, s0
	s_mul_i32 s0, s0, s9
	s_mov_b32 s1, 1
	s_branch .LBB0_15

;     __device__ __forceinline__ void operator()(const f32x4 (&acc)[2][2][4][2], const Unit& u, int wr, int wc, int fr, int fq) const {
;     ...
;         const int col0 = u.pn * BM + wc * 32 + 8 * fq;
;         f32x4 gv[2][2]; unsigned hmp[2][2][2];
; #pragma unroll
;         for (int bj = 0; bj < 2; ++bj)
; #pragma unroll
;             for (int n = 0; n < 2; ++n) {
;                 gv[bj][n] = *(const f32x4*)(gp + col0 + bj * HALF + n * 4) * coef;
;                 { const f32x4 hm_ = *(const f32x4*)(ng + col0 + bj * HALF + n * 4) * (*(const f32x4*)(nsc + col0 + bj * HALF + n * 4) + 1.0f); hmp[bj][n][0] = cvt_pk_bf16(hm_[0], hm_[1]); hmp[bj][n][1] = cvt_pk_bf16(hm_[2], hm_[3]); }
;             }
;         const float* base = fx ? ((r00 < 32768) ? xp : xs - (size_t)32768 * 1024) : out;
;         f32x4 xq[2][4];
;     ...
;         RES_LOAD(0, xq[0]); RES_LOAD(1, xq[1]);
; #pragma unroll
;         for (int it = 0; it < 8; ++it) {
;             const int ai = it >> 2, m = it & 3;
;             const int row = r00 + ai * HALF + wr * 64 + m * 16 + fr;
;             const size_t off = (size_t)row * 1024 + col0;
;             float sq = 0.f;
; #pragma unroll
;             for (int bj = 0; bj < 2; ++bj) {
;                 const f32x4 x0 = xq[it & 1][2 * bj], x1 = xq[it & 1][2 * bj + 1];
;                 const f32x4 o0 = x0 + gv[bj][0] * acc[ai][bj][m][0], o1 = x1 + gv[bj][1] * acc[ai][bj][m][1];
;                 *(f32x4*)(out + off + bj * HALF) = o0; *(f32x4*)(out + off + bj * HALF + 4) = o1;
;                 if (has_next) {
;                     sq += ((o0[0] * o0[0] + o0[1] * o0[1]) + (o0[2] * o0[2] + o0[3] * o0[3])) + ((o1[0] * o1[0] + o1[1] * o1[1]) + (o1[2] * o1[2] + o1[3] * o1[3]));
;                     const f32x4 hm0 = (f32x4){__uint_as_float(hmp[bj][0][0] << 16), __uint_as_float(hmp[bj][0][0] & 0xffff0000u), __uint_as_float(hmp[bj][0][1] << 16), __uint_as_float(hmp[bj][0][1] & 0xffff0000u)};
;                     const f32x4 hm1 = (f32x4){__uint_as_float(hmp[bj][1][0] << 16), __uint_as_float(hmp[bj][1][0] & 0xffff0000u), __uint_as_float(hmp[bj][1][1] << 16), __uint_as_float(hmp[bj][1][1] & 0xffff0000u)};
;                     const f32x4 h0 = o0 * hm0, h1 = o1 * hm1;
;                     u32x4 w; w.x = cvt_pk_bf16(h0[0], h0[1]); w.y = cvt_pk_bf16(h0[2], h0[3]); w.z = cvt_pk_bf16(h1[0], h1[1]); w.w = cvt_pk_bf16(h1[2], h1[3]);
.LBB0_325:
	s_lshl_b32 s21, s1, 8
	s_add_i32 s11, s21, 0xffff8000
	s_lshr_b32 s11, s11, 12
	s_ashr_i32 s10, s1, 3
	s_add_i32 s11, s11, 16
	s_cmpk_lt_i32 s1, 0x80
	s_cselect_b32 s10, s10, s11
	v_readlane_b32 s11, v254, 0
	v_readlane_b32 s1, v253, 63
	s_cselect_b32 s40, s69, s11
	s_mul_i32 s11, s28, 24
	s_cselect_b32 s1, s68, s1
	s_add_i32 s11, s10, s11
	s_mul_hi_i32 s41, s11, 9
	s_mul_i32 s11, s11, 9
	s_add_u32 s46, s11, s16
	s_addc_u32 s47, s41, 0
	s_lshl_b64 s[46:47], s[46:47], 12
	v_lshl_or_b32 v190, s9, 8, v238
	s_add_u32 s46, s18, s46
	v_ashrrev_i32_e32 v191, 31, v190
	s_addc_u32 s47, s19, s47
	v_lshlrev_b64 v[128:129], 2, v[190:191]
	v_lshl_add_u64 v[130:131], s[46:47], 0, v[128:129]
	s_mov_b64 s[46:47], 0x2000
	s_movk_i32 s9, 0x2000
	v_lshl_add_u64 v[144:145], v[130:131], 0, s[46:47]
	v_add_co_u32_e32 v130, vcc, s9, v130
	s_add_i32 s10, s95, s10
	s_nop 0
	v_addc_co_u32_e32 v131, vcc, 0, v131, vcc
	s_nop 0
	s_mul_hi_i32 s11, s10, 9
	s_mul_i32 s10, s10, 9
	s_add_u32 s64, s10, s17
	s_addc_u32 s65, s11, 0
	s_lshl_b64 s[64:65], s[64:65], 12
	s_add_u32 s64, s18, s64
	s_addc_u32 s65, s19, s65
	v_lshl_add_u64 v[134:135], s[64:65], 0, v[128:129]
	s_mov_b64 s[46:47], 0x1000
	s_movk_i32 s9, 0x1000
	v_lshl_add_u64 v[148:149], v[134:135], 0, s[46:47]
	v_add_co_u32_e32 v134, vcc, s9, v134
	v_lshl_add_u64 v[146:147], s[56:57], 0, v[128:129]
	s_nop 0
	v_addc_co_u32_e32 v135, vcc, 0, v135, vcc
	v_mov_b32_e32 v183, v182
	s_nop 0
	v_add_u32_e32 v214, s21, v175
	s_and_b64 s[46:47], s[36:37], exec
	v_ashrrev_i32_e32 v215, 31, v214
	s_cselect_b32 s41, s5, s40
	s_cselect_b32 s40, s4, s1
	v_or_b32_e32 v216, 16, v214
	v_ashrrev_i32_e32 v217, 31, v216
	v_lshlrev_b64 v[208:209], 10, v[214:215]
	v_lshl_add_u64 v[208:209], v[208:209], 0, v[190:191]
	v_lshl_add_u64 v[218:219], v[208:209], 1, s[52:53]
	v_lshl_add_u64 v[220:221], v[208:209], 2, s[4:5]
	v_mov_b32_e32 v244, 0
	s_andn2_b64 vcc, exec, s[54:55]
	global_load_dwordx4 v[130:133], v[144:145], off
	global_load_dwordx4 v[134:137], v[148:149], off
	global_load_dwordx4 v[200:203], v[146:147], off
	global_load_dwordx4 v[204:207], v[144:145], off offset:16
	global_load_dwordx4 v[152:155], v[146:147], off offset:16
	global_load_dwordx4 v[156:159], v[148:149], off offset:16
	s_waitcnt vmcnt(0)
	v_pk_mul_f32 v[192:193], v[182:183], v[132:133]
	v_pk_mul_f32 v[194:195], v[184:185], v[130:131]
	v_pk_add_f32 v[136:137], v[136:137], 1.0 op_sel_hi:[1,0]
	v_pk_add_f32 v[134:135], v[134:135], 1.0 op_sel_hi:[1,0]
	v_pk_mul_f32 v[198:199], v[182:183], v[206:207]
	v_pk_mul_f32 v[196:197], v[184:185], v[204:205]
	v_pk_mul_f32 v[202:203], v[202:203], v[136:137]
	v_pk_mul_f32 v[200:201], v[200:201], v[134:135]
	v_pk_add_f32 v[158:159], v[158:159], 1.0 op_sel_hi:[1,0]
	v_pk_add_f32 v[156:157], v[156:157], 1.0 op_sel_hi:[1,0]
	v_cvt_pk_bf16_f32 v210, v200, v201
	v_cvt_pk_bf16_f32 v211, v202, v203
	v_pk_mul_f32 v[154:155], v[154:155], v[158:159]
	v_pk_mul_f32 v[152:153], v[152:153], v[156:157]
	global_load_dwordx4 v[136:139], v[144:145], off offset:512
	global_load_dwordx4 v[140:143], v[144:145], off offset:528
	global_load_dwordx4 v[130:133], v[146:147], off offset:512
	global_load_dwordx4 v[200:203], v[148:149], off offset:512
	global_load_dwordx4 v[204:207], v[146:147], off offset:528
	v_cvt_pk_bf16_f32 v212, v152, v153
	v_cvt_pk_bf16_f32 v213, v154, v155
	global_load_dwordx4 v[152:155], v[148:149], off offset:528
	s_waitcnt vmcnt(0)
	v_pk_add_f32 v[202:203], v[202:203], 1.0 op_sel_hi:[1,0]
	v_pk_add_f32 v[200:201], v[200:201], 1.0 op_sel_hi:[1,0]
	v_pk_add_f32 v[152:153], v[152:153], 1.0 op_sel_hi:[1,0]
	v_pk_add_f32 v[154:155], v[154:155], 1.0 op_sel_hi:[1,0]
	v_pk_mul_f32 v[132:133], v[132:133], v[202:203]
	v_pk_mul_f32 v[130:131], v[130:131], v[200:201]
	v_pk_mul_f32 v[204:205], v[204:205], v[152:153]
	v_pk_mul_f32 v[206:207], v[206:207], v[154:155]
	v_cvt_pk_bf16_f32 v240, v130, v131
	v_cvt_pk_bf16_f32 v241, v132, v133
	v_cvt_pk_bf16_f32 v243, v204, v205
	v_cvt_pk_bf16_f32 v242, v206, v207
	v_lshlrev_b64 v[130:131], 12, v[214:215]
	v_lshl_add_u64 v[130:131], s[40:41], 0, v[130:131]
	v_lshl_add_u64 v[130:131], v[130:131], 0, v[128:129]
	global_load_dwordx4 v[200:203], v[130:131], off offset:16
	global_load_dwordx4 v[204:207], v[130:131], off
	global_load_dwordx4 v[152:155], v[130:131], off offset:528
	global_load_dwordx4 v[156:159], v[130:131], off offset:512
	v_lshlrev_b64 v[130:131], 12, v[216:217]
	v_lshl_add_u64 v[130:131], s[40:41], 0, v[130:131]
	v_lshl_add_u64 v[132:133], v[130:131], 0, v[128:129]
	global_load_dwordx4 v[144:147], v[132:133], off offset:16
	global_load_dwordx4 v[148:151], v[132:133], off
	global_load_dwordx4 v[128:131], v[132:133], off offset:528
	s_nop 0
	global_load_dwordx4 v[132:135], v[132:133], off offset:512
	s_waitcnt vmcnt(7)
	v_pk_fma_f32 v[120:121], v[120:121], v[196:197], v[200:201]
	v_cndmask_b32_e64 v200, 0, 1, s[54:55]
	s_waitcnt vmcnt(6)
	v_pk_fma_f32 v[126:127], v[126:127], v[192:193], v[206:207]
	v_pk_fma_f32 v[124:125], v[124:125], v[194:195], v[204:205]
	v_pk_fma_f32 v[122:123], v[122:123], v[198:199], v[202:203]
	v_cmp_ne_u32_e64 s[46:47], 1, v200
	v_lshlrev_b32_e32 v200, 16, v210
	v_and_b32_e32 v201, 0xffff0000, v210
	v_lshlrev_b32_e32 v204, 16, v211
	v_and_b32_e32 v205, 0xffff0000, v211
	v_lshlrev_b32_e32 v202, 16, v212
	v_and_b32_e32 v203, 0xffff0000, v212
	v_lshlrev_b32_e32 v206, 16, v213
	v_and_b32_e32 v207, 0xffff0000, v213
	global_store_dwordx4 v[220:221], v[124:127], off
	global_store_dwordx4 v[220:221], v[120:123], off offset:16
	s_cbranch_vccnz .LBB0_327
	v_mov_b32_e32 v210, v125
	v_mov_b32_e32 v211, v121
	v_mov_b32_e32 v208, v124
	v_mov_b32_e32 v209, v120
	v_pk_mul_f32 v[210:211], v[210:211], v[210:211]
	v_mov_b32_e32 v212, v127
	v_mov_b32_e32 v213, v123
	v_pk_fma_f32 v[208:209], v[208:209], v[208:209], v[210:211]
	v_mov_b32_e32 v210, v126
	v_mov_b32_e32 v211, v122
	v_pk_mul_f32 v[212:213], v[212:213], v[212:213]
	v_pk_mul_f32 v[126:127], v[126:127], v[204:205]
	v_pk_fma_f32 v[210:211], v[210:211], v[210:211], v[212:213]
	v_pk_mul_f32 v[124:125], v[124:125], v[200:201]
	v_pk_add_f32 v[208:209], v[208:209], v[210:211]
	s_nop 0
	v_add_f32_e32 v244, v208, v209
	v_pk_mul_f32 v[208:209], v[122:123], v[206:207]
	v_pk_mul_f32 v[122:123], v[120:121], v[202:203]
	v_cvt_pk_bf16_f32 v120, v124, v125
	v_cvt_pk_bf16_f32 v121, v126, v127
	s_nop 0
	v_cvt_pk_bf16_f32 v122, v122, v123
	v_cvt_pk_bf16_f32 v123, v208, v209
	global_store_dwordx4 v[218:219], v[120:123], off
